# SSD item: static s_setprio 1 for waves 4-7 (second head)
# baseline (speedup 1.0000x reference)
; DI void phase_mix(const Params& P, unsigned char* smem) {
;     ...
;     for (int it = blockIdx.x; it < NIT; it += gridDim.x) {
;         int r = it;
;         if (r < I_SSD) { ssd_pair_item(P, smem, r >> 4, r & 15); __syncthreads(); continue; } r -= I_SSD;
.LBB0_235:
	s_setprio 0
	s_barrier

; DI int opaque_tid() { int t = threadIdx.x; asm volatile("" : "+v"(t)); return t; }
; DI void ssd_pair_item(const Params& P, unsigned char* smem, int b, int hp) {
;     const int tid0 = opaque_tid();
;     const int hd = 2 * hp + (tid0 >> 8), g = hp >> 2;
;     const float Aneg = -__expf(P.a_log[hd]), dtb = P.dt_bias[hd], Dsk = P.d_skip[hd];
;     const bf16_t* pbase = P_proj + (size_t)b * TT * LDP;
;     unsigned char* hb = smem + S2_HALF0 + (tid0 >> 8) * S2_HSTRIDE;
;     float* cum = (float*)(hb + S2_CUM); float* wsc = (float*)(hb + S2_WSC); float* dtv = (float*)(hb + S2_DTV); float* wcv = (float*)(hb + S2_WCV);
;     ...
;     __syncthreads();
;     for (int i = (tid0 & 255); i < 5 * 64; i += 256) { const int k = i >> 6, c = i & 63; const int ch = hd * 64 + c; wcv[i] = (k < 4) ? P.conv_w[k * 3072 + ch] : P.conv_b[ch]; }
.LBB0_275:
	s_andn2_b64 vcc, exec, s[2:3]
	s_cbranch_vccnz .LBB0_236
	v_mov_b32_e32 v188, v215
	v_readfirstlane_b32 s32, v215
	s_cmpk_lt_u32 s32, 0x100
	s_cbranch_scc1 .Lssd_prio_done
	s_setprio 1
.Lssd_prio_done:
	s_and_b32 s33, s96, 15
	s_and_b32 s0, s95, 15
	v_ashrrev_i32_e32 v4, 8, v188
	v_lshl_add_u32 v154, s33, 1, v4
	v_ashrrev_i32_e32 v155, 31, v154
	v_lshlrev_b64 v[0:1], 2, v[154:155]
	v_lshl_add_u64 v[2:3], s[24:25], 0, v[0:1]
	global_load_dword v6, v[2:3], off
	v_lshl_add_u64 v[2:3], s[22:23], 0, v[0:1]
	v_lshl_add_u64 v[0:1], s[26:27], 0, v[0:1]
	global_load_dword v189, v[2:3], off
	global_load_dword v156, v[0:1], off
	v_mul_i32_i24_e32 v190, 0xb800, v4
	v_and_b32_e32 v8, 0xff, v188
	v_lshl_or_b32 v2, v8, 2, v190
	v_add_u32_e32 v9, s88, v2
	v_bfe_u32 v2, v188, 6, 2
	s_lshl_b32 s0, s0, 7
	v_mul_u32_u24_e32 v2, 0xc00, v2
	v_lshlrev_b32_e32 v3, 6, v4
	v_lshlrev_b32_e32 v158, 6, v154
	v_and_b32_e32 v7, 63, v188
	v_add3_u32 v2, v2, s0, v3
	v_or_b32_e32 v0, v158, v7
	v_or_b32_e32 v2, v2, v7
	v_ashrrev_i32_e32 v1, 31, v0
	v_ashrrev_i32_e32 v3, 31, v2
	v_lshl_add_u64 v[0:1], v[0:1], 2, s[20:21]
	v_lshl_add_u64 v[2:3], v[2:3], 2, s[18:19]
	s_mov_b64 s[2:3], 0
	s_barrier
	s_branch .LBB0_278
